# seams P1/P2/P5/P7 synchronise only the 4 workgroups of a column group (row panels never leave it); P4-done counter guards the ACT-over-PROJ aliasing before P7
# speedup vs baseline: 1.0324x; 1.0111x over previous
.Lsd1_fast:
	v_readlane_b32 s2, v249, 33
	s_lshl_b32 s2, s2, 8
	s_add_u32 s2, s88, s2
	s_addc_u32 s3, s89, 0
	s_bfe_u32 s7, s94, 0x30003
	s_lshl_b32 s7, s7, 2
	s_add_i32 s7, s7, 0x1004
	v_mov_b32_e32 v1, s7
	s_add_i32 s7, s7, 0x1000
	v_mov_b32_e32 v3, 1
	global_atomic_add v3, v1, v3, s[2:3] offset:1024 sc0
	s_waitcnt vmcnt(0)
	v_readfirstlane_b32 s4, v3
	v_mov_b32_e32 v0, s7
	s_lshr_b32 s5, s4, 2
	s_add_i32 s4, s4, 1
	s_and_b32 s4, s4, 3
	s_cmp_eq_u32 s4, 0
	s_cbranch_scc1 .Lsd1_last
	s_mov_b32 s6, 0

.Lsd3_fast:
	v_readlane_b32 s2, v249, 33
	s_lshl_b32 s2, s2, 8
	s_add_u32 s2, s88, s2
	s_addc_u32 s3, s89, 0
	v_mov_b32_e32 v1, 0x1000
	s_mov_b32 s7, 0x2000
	v_mov_b32_e32 v3, 1
	global_atomic_add v3, v1, v3, s[2:3] offset:1024 sc0
	s_waitcnt vmcnt(0)
	v_readfirstlane_b32 s4, v3
	v_mov_b32_e32 v0, s7
	s_lshr_b32 s5, s4, 5
	s_add_i32 s4, s4, 1
	s_and_b32 s4, s4, 31
	s_cmp_eq_u32 s4, 0
	s_cbranch_scc1 .Lsd3_last
	s_mov_b32 s6, 0

.Lsd4_fast:
	v_mov_b32_e32 v0, 0
	v_mov_b32_e32 v3, 1
	global_atomic_add v0, v3, s[88:89] offset:896
	v_readlane_b32 s2, v249, 33
	s_lshl_b32 s2, s2, 8
	s_add_u32 s2, s88, s2
	s_addc_u32 s3, s89, 0
	v_mov_b32_e32 v1, 0x1000
	s_mov_b32 s7, 0x2000
	v_mov_b32_e32 v3, 1
	global_atomic_add v3, v1, v3, s[2:3] offset:1024 sc0
	s_waitcnt vmcnt(0)
	v_readfirstlane_b32 s4, v3
	v_mov_b32_e32 v0, s7
	s_lshr_b32 s5, s4, 5
	s_add_i32 s4, s4, 1
	s_and_b32 s4, s4, 31
	s_cmp_eq_u32 s4, 0
	s_cbranch_scc1 .Lsd4_last
	s_mov_b32 s6, 0

.Lsd5_fast:
	v_mov_b32_e32 v0, 0
	s_mov_b32 s6, 0
.Lsd5_p4poll:
	global_load_dword v2, v0, s[88:89] offset:896 sc1
	s_waitcnt vmcnt(0)
	v_cmp_le_u32_e32 vcc, 0x100, v2
	s_cbranch_vccnz .Lsd5_p4ok
	s_sleep 1
	s_add_i32 s6, s6, 1
	s_cmp_lt_u32 s6, 0x40000
	s_cbranch_scc1 .Lsd5_p4poll
